# diff attention bias path: packed adds follow the bias reads' arrival order with counted lgkmcnt waits (15/7/0) instead of one full wait; on top of zero-once + MLA K read-ahead
# speedup vs baseline: 1.0056x; 1.0056x over previous
; __device__ __forceinline__ int crow(int r, int hi) { return (r & 3) + 8 * (r >> 2) + 4 * hi; }
; template <int DQK, int DV, bool HAS_BIAS>
; __device__ __forceinline__ void attn_tile(AttnState<DQK, DV>& st, const LAS unsigned char* Kt, const LAS unsigned char* Vt, int bias_mode, const LAS float* tab, int rel0, int nkeys, bool first, LAS float* wsf, int lane) {
;     ...
;     if (HAS_BIAS && bias_mode == 2) {
;         asm volatile("" ::: "memory");
; #pragma unroll
;         for (int r = 0; r < 16; ++r) {
;             const int k = crow(r, hi);
;             const int i0 = min(max(rel0 + k + 128, 0), 191), i1 = min(max(rel0 + k + 160, 0), 191);
;             p0[r] = tab[i0] + st.negm[r]; p1[r] = tab[i1] + st.negm[r];
;         }
;         p0 = __builtin_amdgcn_mfma_f32_32x32x16_bf16(ka[0], st.qf[0], p0, 0, 0, 0);
;         p1 = __builtin_amdgcn_mfma_f32_32x32x16_bf16(kb[0], st.qf[0], p1, 0, 0, 0);
.LBB0_525:
	s_andn2_b64 vcc, exec, s[2:3]
	s_cbranch_vccnz .LBB0_527
	s_nop 6
	v_lshl_add_u32 v224, s58, 2, v225
	ds_read_b32 v80, v224 offset:0
	ds_read_b32 v96, v224 offset:128
	ds_read_b32 v81, v224 offset:4
	ds_read_b32 v97, v224 offset:132
	ds_read_b32 v82, v224 offset:8
	ds_read_b32 v98, v224 offset:136
	ds_read_b32 v83, v224 offset:12
	ds_read_b32 v99, v224 offset:140
	ds_read_b32 v84, v224 offset:32
	ds_read_b32 v100, v224 offset:160
	ds_read_b32 v85, v224 offset:36
	ds_read_b32 v101, v224 offset:164
	ds_read_b32 v86, v224 offset:40
	ds_read_b32 v102, v224 offset:168
	ds_read_b32 v87, v224 offset:44
	ds_read_b32 v103, v224 offset:172
	ds_read_b32 v88, v224 offset:64
	ds_read_b32 v104, v224 offset:192
	ds_read_b32 v89, v224 offset:68
	ds_read_b32 v105, v224 offset:196
	ds_read_b32 v90, v224 offset:72
	ds_read_b32 v106, v224 offset:200
	ds_read_b32 v91, v224 offset:76
	ds_read_b32 v107, v224 offset:204
	ds_read_b32 v92, v224 offset:96
	ds_read_b32 v108, v224 offset:224
	ds_read_b32 v93, v224 offset:100
	ds_read_b32 v109, v224 offset:228
	ds_read_b32 v94, v224 offset:104
	ds_read_b32 v110, v224 offset:232
	ds_read_b32 v95, v224 offset:108
	ds_read_b32 v111, v224 offset:236
	s_waitcnt lgkmcnt(15)
	v_pk_add_f32 v[80:81], v[64:65], v[80:81]
	v_pk_add_f32 v[96:97], v[64:65], v[96:97]
	v_pk_add_f32 v[82:83], v[66:67], v[82:83]
	v_pk_add_f32 v[98:99], v[66:67], v[98:99]
	v_pk_add_f32 v[84:85], v[68:69], v[84:85]
	v_pk_add_f32 v[100:101], v[68:69], v[100:101]
	v_pk_add_f32 v[86:87], v[70:71], v[86:87]
	v_pk_add_f32 v[102:103], v[70:71], v[102:103]
	s_waitcnt lgkmcnt(7)
	v_pk_add_f32 v[88:89], v[72:73], v[88:89]
	v_pk_add_f32 v[104:105], v[72:73], v[104:105]
	v_pk_add_f32 v[90:91], v[74:75], v[90:91]
	v_pk_add_f32 v[106:107], v[74:75], v[106:107]
	s_waitcnt lgkmcnt(0)
	v_pk_add_f32 v[92:93], v[76:77], v[92:93]
	v_pk_add_f32 v[94:95], v[78:79], v[94:95]
	v_pk_add_f32 v[108:109], v[76:77], v[108:109]
	v_pk_add_f32 v[110:111], v[78:79], v[110:111]
	s_waitcnt vmcnt(6)
	v_mfma_f32_32x32x16_bf16 v[80:95], v[180:183], v[112:115], v[80:95]
	v_mfma_f32_32x32x16_bf16 v[96:111], v[176:179], v[112:115], v[96:111]

; __device__ __forceinline__ int crow(int r, int hi) { return (r & 3) + 8 * (r >> 2) + 4 * hi; }
; template <int DQK, int DV, bool HAS_BIAS>
; __device__ __forceinline__ void attn_tile(AttnState<DQK, DV>& st, const LAS unsigned char* Kt, const LAS unsigned char* Vt, int bias_mode, const LAS float* tab, int rel0, int nkeys, bool first, LAS float* wsf, int lane) {
;     ...
;     if (HAS_BIAS && bias_mode == 2) {
;         asm volatile("" ::: "memory");
; #pragma unroll
;         for (int r = 0; r < 16; ++r) {
;             const int k = crow(r, hi);
;             const int i0 = min(max(rel0 + k + 128, 0), 191), i1 = min(max(rel0 + k + 160, 0), 191);
;             p0[r] = tab[i0] + st.negm[r]; p1[r] = tab[i1] + st.negm[r];
;         }
;         p0 = __builtin_amdgcn_mfma_f32_32x32x16_bf16(ka[0], st.qf[0], p0, 0, 0, 0);
;         p1 = __builtin_amdgcn_mfma_f32_32x32x16_bf16(kb[0], st.qf[0], p1, 0, 0, 0);
.LBB0_545:
	s_andn2_b64 vcc, exec, s[2:3]
	s_cbranch_vccnz .LBB0_547
	s_nop 6
	v_lshl_add_u32 v224, s58, 2, v225
	ds_read_b32 v80, v224 offset:256
	ds_read_b32 v96, v224 offset:384
	ds_read_b32 v81, v224 offset:260
	ds_read_b32 v97, v224 offset:388
	ds_read_b32 v82, v224 offset:264
	ds_read_b32 v98, v224 offset:392
	ds_read_b32 v83, v224 offset:268
	ds_read_b32 v99, v224 offset:396
	ds_read_b32 v84, v224 offset:288
	ds_read_b32 v100, v224 offset:416
	ds_read_b32 v85, v224 offset:292
	ds_read_b32 v101, v224 offset:420
	ds_read_b32 v86, v224 offset:296
	ds_read_b32 v102, v224 offset:424
	ds_read_b32 v87, v224 offset:300
	ds_read_b32 v103, v224 offset:428
	ds_read_b32 v88, v224 offset:320
	ds_read_b32 v104, v224 offset:448
	ds_read_b32 v89, v224 offset:324
	ds_read_b32 v105, v224 offset:452
	ds_read_b32 v90, v224 offset:328
	ds_read_b32 v106, v224 offset:456
	ds_read_b32 v91, v224 offset:332
	ds_read_b32 v107, v224 offset:460
	ds_read_b32 v92, v224 offset:352
	ds_read_b32 v108, v224 offset:480
	ds_read_b32 v93, v224 offset:356
	ds_read_b32 v109, v224 offset:484
	ds_read_b32 v94, v224 offset:360
	ds_read_b32 v110, v224 offset:488
	ds_read_b32 v95, v224 offset:364
	ds_read_b32 v111, v224 offset:492
	s_waitcnt lgkmcnt(15)
	v_pk_add_f32 v[80:81], v[64:65], v[80:81]
	v_pk_add_f32 v[96:97], v[64:65], v[96:97]
	v_pk_add_f32 v[82:83], v[66:67], v[82:83]
	v_pk_add_f32 v[98:99], v[66:67], v[98:99]
	v_pk_add_f32 v[84:85], v[68:69], v[84:85]
	v_pk_add_f32 v[100:101], v[68:69], v[100:101]
	v_pk_add_f32 v[86:87], v[70:71], v[86:87]
	v_pk_add_f32 v[102:103], v[70:71], v[102:103]
	s_waitcnt lgkmcnt(7)
	v_pk_add_f32 v[88:89], v[72:73], v[88:89]
	v_pk_add_f32 v[104:105], v[72:73], v[104:105]
	v_pk_add_f32 v[90:91], v[74:75], v[90:91]
	v_pk_add_f32 v[106:107], v[74:75], v[106:107]
	s_waitcnt lgkmcnt(0)
	v_pk_add_f32 v[92:93], v[76:77], v[92:93]
	v_pk_add_f32 v[94:95], v[78:79], v[94:95]
	v_pk_add_f32 v[108:109], v[76:77], v[108:109]
	v_pk_add_f32 v[110:111], v[78:79], v[110:111]
	v_mfma_f32_32x32x16_bf16 v[80:95], v[180:183], v[112:115], v[80:95]
	s_nop 0
	v_mfma_f32_32x32x16_bf16 v[96:111], v[176:179], v[112:115], v[96:111]
